# v35 + same half-tile start stagger in second ffn_in phase
# speedup vs baseline: 1.0326x; 1.0020x over previous
; DEV void phase_ffn_in(const Params& p, const bf16_t* wt, char* smem) {
;   const bf16_t* xb = (const bf16_t*)(p.ws + O_XB);
;   bf16_t* h = (bf16_t*)(p.ws + O_H);
;   const int nct = 44;
;   int rt, ct;
;   for (int it = 0; tile_map(it, nct, rt, ct); ++it) {
.LBB0_3198:
	v_readlane_b32 vcc_lo, v250, 0
	s_nop 3
	s_cmp_lt_u32 vcc_lo, 0x100
	s_cbranch_scc1 .Lstag3198
	s_sleep 127
	s_sleep 127
	s_sleep 127
	s_sleep 127
	s_sleep 127
	s_sleep 127
